# phase 8 GEMM: row-major swizzled LDS tile image (full cache-line LDS-DMA) and per-workgroup rotated K start
# speedup vs baseline: 1.0732x; 1.0139x over previous
;     __device__ __forceinline__ bool next(int i, Unit& u) const { if (i != 0 || c >= n) return false; u.pm = 0; u.pn = c; u.kt0 = 0; u.nkt = ntk; u.piece = -1; return true; }
; #define PG8_WAIT_V(n) asm volatile("s_waitcnt vmcnt(" #n ")" ::: "memory")
; #define PG8_BAR __builtin_amdgcn_s_barrier()
; template <class Epi, class Sched>
; __device__ __forceinline__ void gemm_phase(LAS unsigned char* lds, const Gemm g, const Sched& S, const Epi& E) {
;     const int tid = threadIdx.x, wid = __builtin_amdgcn_readfirstlane(tid >> 6), lane = tid & 63, wr = wid >> 2, wc = wid & 3, fr = lane & 15, fq = lane >> 4;
;     unsigned voffA[2], voffB[2];
; #pragma unroll
;     for (int i = 0; i < 2; ++i) { int R, C; stage_rc(tid * 16 + i * 8192, R, C); const int Rb = Epi::PERM ? ((R & ~31) + perm32(R & 31)) : R;
;         voffA[i] = (unsigned)(R * g.lda + C) * 2u; voffB[i] = (unsigned)(Rb * g.ldb + C) * 2u; }
;     const size_t kstep = (size_t)(BK * 2);
;     const size_t hstepA = g.a_half ? g.a_half : (size_t)HALF * g.lda * 2, hstepB = g.b_half ? g.b_half : (size_t)HALF * g.ldb * 2;
;     const size_t tstepA = g.a_tile ? g.a_tile : (size_t)BM * g.lda * 2, tstepB = g.b_tile ? g.b_tile : (size_t)BM * g.ldb * 2;
;     const unsigned ldsw = (unsigned)wid * 1024u;
;     const int aoff = lds_byte(wr * 64 + fr, fq * 8), boff = lds_byte(wc * 32 + fr, fq * 8);
;     ...
;     Unit cur, nxt; int ui = 0;
;     if (!S.next(0, cur)) return;
;     f32x4 acc[2][2][4][2];
; #pragma unroll
;     for (int a = 0; a < 2; ++a)
; #pragma unroll
;         for (int b = 0; b < 2; ++b)
; #pragma unroll
;             for (int m = 0; m < 4; ++m)
; #pragma unroll
;                 for (int n = 0; n < 2; ++n) acc[a][b][m][n] = (f32x4){0.f, 0.f, 0.f, 0.f};
;     bf16x8 At[4][2], B0[2][2], B1[2][2];
;     const char* cA = (const char*)g.A + (size_t)cur.pm * tstepA + (size_t)cur.pn * g.a_pn_off + (size_t)cur.kt0 * kstep; const char* cB = (const char*)g.Bt + (size_t)cur.pn * tstepB + (size_t)cur.kt0 * kstep;
;     PG8_STAGE(PG8_SB(0, 0), cB, voffB); PG8_STAGE(PG8_SA(0, 0), cA, voffA); PG8_STAGE(PG8_SB(0, 1), cB + hstepB, voffB); PG8_STAGE(PG8_SA(0, 1), cA + hstepA, voffA);
;     if (wr == 1) PG8_BAR;
;     PG8_WAIT_V(4); PG8_BAR;
;     PG8_STAGE(PG8_SB(1, 0), cB + kstep, voffB); PG8_STAGE(PG8_SA(1, 0), cA + kstep, voffA); PG8_STAGE(PG8_SB(1, 1), cB + hstepB + kstep, voffB);
;     PG8_WAIT_V(6); PG8_BAR;
.LBB0_1377:
	s_cmp_lt_i32 s86, 9
	s_cselect_b64 s[4:5], -1, 0
	s_and_b64 s[4:5], s[4:5], s[6:7]
	s_andn2_b64 vcc, exec, s[4:5]
	s_cbranch_vccnz .LBB0_1592
	v_lshlrev_b32_e32 v87, 4, v160
	v_lshrrev_b32_e32 v86, 3, v160
	s_cmpk_gt_i32 s2, 0x43f
	v_readfirstlane_b32 s3, v160
	s_cbranch_scc1 .LBB0_1390
	s_waitcnt vmcnt(0)
	v_lshrrev_b32_e32 v1, 1, v160
	v_and_b32_e32 v0, 32, v160
	v_and_b32_e32 v11, 24, v1
	v_lshrrev_b32_e32 v1, 5, v160
	s_add_u32 s30, s84, 0x7f39000
	v_bfe_u32 v10, v160, 2, 4
	v_bitop3_b32 v8, v87, v0, 48 bitop3:0x6c
	v_and_b32_e32 v9, 64, v160
	v_and_b32_e32 v1, 4, v1
	v_bfe_u32 v2, v160, 2, 2
	s_movk_i32 s4, 0x70
	s_addc_u32 s31, s85, 0
	v_or_b32_e32 v0, v8, v9
	v_or3_b32 v1, v1, v2, v11
	v_and_or_b32 v2, v86, s4, v10
	s_movk_i32 s4, 0x60
	v_add_u32_e32 v12, 0x2000, v87
	s_add_u32 s34, s84, 0x6f00000
	v_and_or_b32 v3, v86, s4, v1
	v_lshl_or_b32 v64, v2, 12, v0
	v_lshrrev_b32_e32 v2, 7, v12
	s_movk_i32 s4, 0xf0
	s_addc_u32 s35, s85, 0
	v_lshl_or_b32 v66, v3, 12, v0
	v_and_or_b32 v3, v2, s4, v10
	s_movk_i32 s4, 0xe0
	s_ashr_i32 s37, s2, 31
	v_and_or_b32 v1, v2, s4, v1
	s_lshr_b32 s4, s37, 29
	s_add_i32 s4, s2, s4
	s_lshr_b32 s7, s3, 6
	s_ashr_i32 s5, s4, 3
	s_and_b32 s4, s4, -8
	s_lshr_b32 s16, s3, 8
	s_lshl_b32 s36, s7, 10
	s_sub_i32 s4, s2, s4
	s_cmp_lt_i32 s4, 0
	s_movk_i32 s38, 0x89
	s_cselect_b32 s6, s38, 0x88
	s_mul_i32 s4, s4, s6
	s_add_i32 s4, s4, s5
	s_ashr_i32 s5, s4, 31
	s_lshr_b32 s5, s5, 25
	s_add_i32 s5, s4, s5
	s_ashr_i32 s5, s5, 7
	s_lshl_b32 s8, s5, 3
	s_sub_i32 s6, 0x44, s8
	s_lshl_b32 s5, s5, 7
	s_min_u32 s9, s6, 8
	s_sub_i32 s10, s4, s5
	v_lshl_or_b32 v70, v1, 12, v0
	s_sext_i32_i8 s4, s10
	v_cvt_f32_ubyte0_e32 v1, s9
	v_lshl_or_b32 v68, v3, 12, v0
	v_cvt_f32_i32_e32 v0, s4
	v_rcp_iflag_f32_e32 v2, v1
	s_ashr_i32 s4, s4, 30
	s_or_b32 s6, s4, 1
	v_mov_b32_e32 v67, 0
	v_mul_f32_e32 v2, v0, v2
	v_trunc_f32_e32 v2, v2
	v_fma_f32 v0, -v2, v1, v0
	v_cvt_i32_f32_e32 v2, v2
	v_cmp_ge_f32_e64 s[4:5], |v0|, v1
	s_and_b64 s[4:5], s[4:5], exec
	s_cselect_b32 s4, s6, 0
	v_readfirstlane_b32 s5, v2
	s_add_i32 s6, s5, s4
	s_mul_i32 s4, s6, s9
	s_sub_i32 s4, s10, s4
	s_sext_i32_i8 s4, s4
	s_add_i32 s24, s8, s4
	s_ashr_i32 s25, s24, 31
	s_bfe_i64 s[8:9], s[6:7], 0x80000
	s_lshl_b64 s[4:5], s[24:25], 19
	s_lshl_b64 s[8:9], s[8:9], 19
	s_add_u32 s28, s34, s8
	s_addc_u32 s29, s35, s9
	s_bfe_u32 s63, s2, 0x30003
	s_lshl_b32 s63, s63, 8
	s_add_u32 s28, s28, s63
	s_addc_u32 s29, s29, 0
	s_add_i32 s25, s36, 0
	v_lshrrev_b32_e32 v210, 3, v160
	v_bfe_u32 v211, v160, 4, 3
	v_and_b32_e32 v212, 7, v160
	v_xor_b32_e32 v212, v212, v211
	v_lshlrev_b32_e32 v212, 4, v212
	v_lshl_or_b32 v64, v210, 12, v212
	v_add_u32_e32 v68, 0x40000, v64
	v_and_b32_e32 v211, 15, v210
	v_bfe_u32 v213, v210, 4, 1
	v_lshrrev_b32_e32 v214, 2, v211
	v_lshlrev_b32_e32 v214, 3, v214
	v_lshl_or_b32 v214, v213, 2, v214
	v_and_b32_e32 v211, 3, v211
	v_or_b32_e32 v214, v214, v211
	v_and_b32_e32 v211, 32, v210
	v_or_b32_e32 v214, v214, v211
	v_lshl_or_b32 v66, v214, 12, v212
	v_add_u32_e32 v70, 0x40000, v66
	s_add_i32 m0, s25, 0x10000
	v_mov_b32_e32 v71, v67
	global_load_lds_dwordx4 v66, s[28:29]
	s_add_i32 m0, s25, 0x12000
	s_add_u32 s26, s30, s4
	global_load_lds_dwordx4 v70, s[28:29]
	s_addc_u32 s27, s31, s5
	s_add_u32 s26, s26, s63
	s_addc_u32 s27, s27, 0
	s_mov_b32 m0, s25
	s_add_i32 s39, s25, 0x2000
	v_lshl_add_u64 v[0:1], s[28:29], 0, v[66:67]
	global_load_lds_dwordx4 v64, s[26:27]
	s_mov_b32 m0, s39
	s_mov_b64 s[4:5], 0x800
	v_mov_b32_e32 v65, v67
	v_lshl_add_u64 v[2:3], s[28:29], 0, v[70:71]
	global_load_lds_dwordx4 v68, s[26:27]
	s_add_i32 m0, s25, 0x14000
	v_lshl_add_u64 v[14:15], v[0:1], 0, s[4:5]
	v_mov_b32_e32 v69, v67
	v_lshl_add_u64 v[6:7], s[26:27], 0, v[64:65]
	global_load_lds_dwordx4 v[14:15], off
	v_lshl_add_u64 v[14:15], v[2:3], 0, s[4:5]
	s_add_i32 m0, s25, 0x16000
	s_add_i32 s40, s25, 0x4000
	v_lshl_add_u64 v[4:5], s[26:27], 0, v[68:69]
	global_load_lds_dwordx4 v[14:15], off
	v_lshl_add_u64 v[14:15], v[6:7], 0, s[4:5]
	s_mov_b32 m0, s40
	s_add_i32 s41, s25, 0x6000
	global_load_lds_dwordx4 v[14:15], off
	v_lshl_add_u64 v[14:15], v[4:5], 0, s[4:5]
	s_mov_b32 m0, s41
	s_movk_i32 s42, 0x2000
	global_load_lds_dwordx4 v[14:15], off
	s_cmp_lg_u32 s16, 1
	s_mov_b32 s43, 0
	s_cbranch_scc1 .LBB0_1381
	s_barrier
.LBB0_1381:
	s_add_u32 s8, s84, 0xa139000
	s_addc_u32 s9, s85, 0
	s_add_u32 s10, s84, 0x11d39000
	s_mov_b64 s[12:13], 0x80
	s_addc_u32 s11, s85, 0
	s_add_i32 m0, s25, 0x18000
	v_lshl_add_u64 v[14:15], v[0:1], 0, s[12:13]
	s_waitcnt vmcnt(4)
	s_barrier
	global_load_lds_dwordx4 v[14:15], off
	v_lshl_add_u64 v[14:15], v[2:3], 0, s[12:13]
	s_add_i32 m0, s25, 0x1a000
	s_add_i32 s44, s25, 0x8000
	global_load_lds_dwordx4 v[14:15], off
	v_lshl_add_u64 v[6:7], v[6:7], 0, s[12:13]
	s_mov_b32 m0, s44
	s_add_i32 s45, s25, 0xa000
	global_load_lds_dwordx4 v[6:7], off
	v_lshl_add_u64 v[4:5], v[4:5], 0, s[12:13]
	s_mov_b32 m0, s45
	s_mov_b64 s[14:15], 0x880
	global_load_lds_dwordx4 v[4:5], off
	s_add_i32 m0, s25, 0x1c000
	v_lshl_add_u64 v[0:1], v[0:1], 0, s[14:15]
	global_load_lds_dwordx4 v[0:1], off
	v_lshl_add_u64 v[0:1], v[2:3], 0, s[14:15]
	s_add_i32 m0, s25, 0x1e000
	s_sext_i32_i8 s51, s6
	global_load_lds_dwordx4 v[0:1], off
	v_and_b32_e32 v0, 15, v160
	v_lshlrev_b32_e32 v1, 1, v11
	v_lshlrev_b32_e32 v2, 6, v160
	s_movk_i32 s6, 0x3c0
	v_and_or_b32 v2, v2, s6, v1
	v_and_b32_e32 v3, 32, v184
	v_lshl_or_b32 v88, s16, 6, v0
	v_lshl_or_b32 v0, v0, 6, v1
	s_lshl_b32 s6, s16, 13
	v_bitop3_b32 v0, v0, s6, v3 bitop3:0xde
	s_lshl_b32 s6, s7, 5
	s_and_b32 s6, s6, 0x60
	s_lshl_b32 s7, s6, 7
	v_lshlrev_b32_e32 v1, 5, v12
	v_bitop3_b32 v89, s7, v2, v3 bitop3:0xf6
	v_and_b32_e32 v1, 0xf0000, v1
	v_lshlrev_b32_e32 v2, 12, v10
	v_or3_b32 v1, v8, v1, v2
	v_add_u32_e32 v72, v1, v9
	v_lshlrev_b32_e32 v1, 9, v160
	s_waitcnt vmcnt(6)
	v_and_b32_e32 v1, 0x70000, v1
	v_or3_b32 v1, v8, v1, v2
	s_add_i32 s47, 0, 0x10000
	s_add_i32 s48, 0, 0x14000
	s_ashr_i32 s46, s96, 31
	v_or_b32_e32 v90, s6, v11
	v_mov_b32_e32 v73, v67
	v_add_u32_e32 v74, v1, v9
	v_mov_b32_e32 v75, v67
	v_mov_b64_e32 v[76:77], 0x440
	v_mov_b64_e32 v[78:79], 0x43f
	v_add_u32_e32 v91, s47, v89
	v_add_u32_e32 v92, 0, v0
	v_add_u32_e32 v93, s48, v89
	s_movk_i32 s49, 0x4a00
	s_movk_i32 s50, 0x3000
	v_mov_b32_e32 v74, v64
	v_mov_b32_e32 v72, v68
	v_and_b32_e32 v210, 15, v160
	v_bfe_u32 v211, v160, 4, 2
	v_lshrrev_b32_e32 v212, 1, v210
	v_xor_b32_e32 v211, v211, v212
	v_lshlrev_b32_e32 v211, 4, v211
	v_lshrrev_b32_e32 v213, 8, v160
	v_lshl_or_b32 v213, v213, 6, v210
	v_lshl_or_b32 v92, v213, 7, v211
	v_xor_b32_e32 v218, 64, v92
	v_bfe_u32 v213, v160, 6, 2
	v_lshl_or_b32 v213, v213, 5, v210
	v_lshl_or_b32 v91, v213, 7, v211
	v_add_u32_e32 v91, 0x10000, v91
	v_xor_b32_e32 v219, 64, v91
	s_sub_u32 s26, s26, s63
	s_subb_u32 s27, s27, 0
	s_sub_u32 s28, s28, s63
	s_subb_u32 s29, s29, 0
	s_barrier

;     __device__ __forceinline__ bool next(int i, Unit& u) const { if (i != 0 || c >= n) return false; u.pm = 0; u.pn = c; u.kt0 = 0; u.nkt = ntk; u.piece = -1; return true; }
; #define PG8_STAGE(bufoff, gbase, voff) do { _Pragma("unroll") for (int _i = 0; _i < 2; ++_i) \
;         __builtin_amdgcn_global_load_lds((const unsigned*)((const char*)(gbase) + (voff)[_i]), (LAS unsigned*)(lds + (bufoff) + ldsw + _i * 8192), 16, 0, 0); } while (0)
; #define PG8_WAIT_V(n) asm volatile("s_waitcnt vmcnt(" #n ")" ::: "memory")
; template <class Epi, class Sched>
; __device__ __forceinline__ void gemm_phase(LAS unsigned char* lds, const Gemm g, const Sched& S, const Epi& E) {
;     ...
;         const bool has_next = S.next(ui + 1, nxt);
;         const char* nA = has_next ? (const char*)g.A + (size_t)nxt.pm * tstepA + (size_t)nxt.pn * g.a_pn_off + (size_t)nxt.kt0 * kstep : cA; const char* nB = has_next ? (const char*)g.Bt + (size_t)nxt.pn * tstepB + (size_t)nxt.kt0 * kstep : cB;
;         const int nt = cur.nkt;
; #pragma unroll 1
;         for (int t = 0; t < nt; t += 2) {
;             const bool last = (t == nt - 2);
;             const char* a1 = cA + (size_t)(t + 1) * kstep;
;             const char* a2 = last ? nA : cA + (size_t)(t + 2) * kstep; const char* b2 = last ? nB : cB + (size_t)(t + 2) * kstep;
;             const char* a3 = a2 + kstep; const char* b3 = b2 + kstep;
;             PG8_LDB(B0, 0, 0); PG8_SCHED; PG8_LDA(At, 0, 0); PG8_STAGE(PG8_SA(1, 1), a1 + hstepA, voffA);
;             PG8_WAIT_L(8); PG8_BAR; PG8_WAIT_L(0); PG8_MMA(0, 0, At, B0); PG8_BAR; PG8_SCHED;
;             PG8_LDB(B1, 0, 1); PG8_STAGE(PG8_SB(0, 0), b2, voffB);
;             PG8_BAR; PG8_WAIT_L(0); if constexpr (!Epi::DIAG) PG8_MMA(0, 1, At, B1); PG8_BAR;
;             PG8_LDA(At, 0, 1); PG8_STAGE(PG8_SA(0, 0), a2, voffA);
;             PG8_BAR; PG8_WAIT_L(0); if constexpr (!Epi::DIAG) PG8_MMA(1, 0, At, B0); PG8_BAR; PG8_SCHED;
;             PG8_STAGE(PG8_SB(0, 1), b2 + hstepB, voffB);
;             PG8_WAIT_V(6); PG8_BAR; PG8_MMA(1, 1, At, B1); PG8_BAR;
;     ...
; #pragma unroll
;         for (int a = 0; a < 2; ++a)
; #pragma unroll
;             for (int b = 0; b < 2; ++b)
; #pragma unroll
;                 for (int m = 0; m < 4; ++m)
; #pragma unroll
;                     for (int n = 0; n < 2; ++n) acc[a][b][m][n] = (f32x4){0.f, 0.f, 0.f, 0.f};
;         cur = nxt; cA = nA; cB = nB; ++ui;
.LBB0_1384:
	s_ashr_i32 s19, s18, 31
	v_cmp_lt_i64_e32 vcc, s[20:21], v[76:77]
	s_lshl_b64 s[20:21], s[18:19], 19
	s_add_u32 s20, s30, s20
	s_addc_u32 s21, s31, s21
	s_and_b64 s[22:23], vcc, exec
	s_cselect_b32 s19, s21, s27
	s_cselect_b32 s52, s20, s26
	s_ashr_i32 s17, s16, 31
	s_lshl_b64 s[22:23], s[16:17], 19
	s_add_u32 s22, s34, s22
	s_addc_u32 s23, s35, s23
	s_and_b64 s[54:55], vcc, exec
	s_cselect_b32 s17, s23, s29
	s_cselect_b32 s53, s22, s28
	s_add_u32 s26, s26, 0x880
	s_addc_u32 s27, s27, 0
	s_add_u32 s28, s28, 0x100
	v_mov_b32_e32 v0, 0
	s_addc_u32 s29, s29, 0
	s_mov_b32 s54, -2
	v_mov_b32_e32 v1, v0
	v_mov_b32_e32 v2, v0
	v_mov_b32_e32 v3, v0
	v_mov_b32_e32 v8, v0
	v_mov_b32_e32 v9, v0
	v_mov_b32_e32 v10, v0
	v_mov_b32_e32 v11, v0
	v_mov_b32_e32 v16, v0
	v_mov_b32_e32 v17, v0
	v_mov_b32_e32 v18, v0
	v_mov_b32_e32 v19, v0
	v_mov_b32_e32 v24, v0
	v_mov_b32_e32 v25, v0
	v_mov_b32_e32 v26, v0
	v_mov_b32_e32 v27, v0
	v_mov_b32_e32 v32, v0
	v_mov_b32_e32 v33, v0
	v_mov_b32_e32 v34, v0
	v_mov_b32_e32 v35, v0
	v_mov_b32_e32 v36, v0
	v_mov_b32_e32 v37, v0
	v_mov_b32_e32 v38, v0
	v_mov_b32_e32 v39, v0
	v_mov_b32_e32 v48, v0
	v_mov_b32_e32 v49, v0
	v_mov_b32_e32 v50, v0
	v_mov_b32_e32 v51, v0
	v_mov_b32_e32 v52, v0
	v_mov_b32_e32 v53, v0
	v_mov_b32_e32 v54, v0
	v_mov_b32_e32 v55, v0
	v_mov_b32_e32 v4, v0
	v_mov_b32_e32 v5, v0
	v_mov_b32_e32 v6, v0
	v_mov_b32_e32 v7, v0
	v_mov_b32_e32 v12, v0
	v_mov_b32_e32 v13, v0
	v_mov_b32_e32 v14, v0
	v_mov_b32_e32 v15, v0
	v_mov_b32_e32 v20, v0
	v_mov_b32_e32 v21, v0
	v_mov_b32_e32 v22, v0
	v_mov_b32_e32 v23, v0
	v_mov_b32_e32 v28, v0
	v_mov_b32_e32 v29, v0
	v_mov_b32_e32 v30, v0
	v_mov_b32_e32 v31, v0
	v_mov_b32_e32 v40, v0
	v_mov_b32_e32 v41, v0
	v_mov_b32_e32 v42, v0
	v_mov_b32_e32 v43, v0
	v_mov_b32_e32 v44, v0
	v_mov_b32_e32 v45, v0
	v_mov_b32_e32 v46, v0
	v_mov_b32_e32 v47, v0
	v_mov_b32_e32 v56, v0
	v_mov_b32_e32 v57, v0
	v_mov_b32_e32 v58, v0
	v_mov_b32_e32 v59, v0
	v_mov_b32_e32 v60, v0
	v_mov_b32_e32 v61, v0
	v_mov_b32_e32 v62, v0
	v_mov_b32_e32 v63, v0
	s_mov_b32 s62, s63
.LBB0_1385:
	ds_read_b128 v[80:83], v91
	ds_read_b128 v[94:97], v219
	ds_read_b128 v[98:101], v91 offset:2048
	ds_read_b128 v[102:105], v219 offset:2048
	s_add_u32 s60, s62, 0x100
	s_and_b32 s60, s60, 0x7ff
	s_add_u32 s55, s26, s60
	s_addc_u32 s56, s27, 0
	s_sub_u32 s55, s55, 0x880
	s_subb_u32 s56, s56, 0
	s_add_u32 s64, s28, s60
	s_addc_u32 s65, s29, 0
	s_sub_u32 s64, s64, 0x100
	s_subb_u32 s65, s65, 0
	s_add_u32 s66, s52, s63
	s_addc_u32 s67, s19, 0
	s_add_u32 s68, s53, s63
	s_addc_u32 s69, s17, 0
	s_cmp_eq_u32 s54, 12
	s_cselect_b32 s57, s67, s56
	s_cselect_b32 s56, s66, s55
	s_cselect_b32 s59, s69, s65
	s_cselect_b32 s58, s68, s64
	ds_read_b128 v[106:109], v92
	ds_read_b128 v[110:113], v218
	ds_read_b128 v[114:117], v92 offset:2048
	ds_read_b128 v[118:121], v218 offset:2048
	ds_read_b128 v[122:125], v92 offset:4096
	ds_read_b128 v[126:129], v218 offset:4096
	ds_read_b128 v[130:133], v92 offset:6144
	ds_read_b128 v[134:137], v218 offset:6144
	s_add_u32 s60, s28, 0x780
	s_addc_u32 s61, s29, 0
	s_add_u32 s60, s60, s62
	s_addc_u32 s61, s61, 0
	s_add_u32 s70, s26, s62
	s_addc_u32 s71, s27, 0
	v_lshl_add_u64 v[84:85], s[60:61], 0, v[66:67]
	s_add_i32 m0, s36, 0x1c000
	s_nop 0
	global_load_lds_dwordx4 v[84:85], off
	v_lshl_add_u64 v[84:85], s[60:61], 0, v[70:71]
	s_add_i32 m0, s36, 0x1e000
	s_nop 0
	global_load_lds_dwordx4 v[84:85], off
	v_lshl_add_u64 v[84:85], s[70:71], 0, v[74:75]
	s_add_i32 m0, s25, 0xc000
	s_nop 0
	global_load_lds_dwordx4 v[84:85], off
	v_lshl_add_u64 v[84:85], s[70:71], 0, v[72:73]
	s_add_i32 m0, s25, 0xe000
	s_nop 0
	global_load_lds_dwordx4 v[84:85], off
	s_waitcnt vmcnt(8)
	s_waitcnt lgkmcnt(0)
	s_barrier
	s_setprio 1
	v_mfma_f32_16x16x32_bf16 v[60:63], v[80:83], v[106:109], v[60:63]
	v_mfma_f32_16x16x32_bf16 v[56:59], v[98:101], v[106:109], v[56:59]
	v_mfma_f32_16x16x32_bf16 v[44:47], v[80:83], v[114:117], v[44:47]
	v_mfma_f32_16x16x32_bf16 v[40:43], v[98:101], v[114:117], v[40:43]
	v_mfma_f32_16x16x32_bf16 v[28:31], v[80:83], v[122:125], v[28:31]
	v_mfma_f32_16x16x32_bf16 v[20:23], v[98:101], v[122:125], v[20:23]
	v_mfma_f32_16x16x32_bf16 v[12:15], v[80:83], v[130:133], v[12:15]
	v_mfma_f32_16x16x32_bf16 v[4:7], v[98:101], v[130:133], v[4:7]
	v_mfma_f32_16x16x32_bf16 v[60:63], v[94:97], v[110:113], v[60:63]
	v_mfma_f32_16x16x32_bf16 v[56:59], v[102:105], v[110:113], v[56:59]
	v_mfma_f32_16x16x32_bf16 v[44:47], v[94:97], v[118:121], v[44:47]
	v_mfma_f32_16x16x32_bf16 v[40:43], v[102:105], v[118:121], v[40:43]
	v_mfma_f32_16x16x32_bf16 v[28:31], v[94:97], v[126:129], v[28:31]
	v_mfma_f32_16x16x32_bf16 v[20:23], v[102:105], v[126:129], v[20:23]
	v_mfma_f32_16x16x32_bf16 v[12:15], v[94:97], v[134:137], v[12:15]
	v_mfma_f32_16x16x32_bf16 v[4:7], v[102:105], v[134:137], v[4:7]
	s_setprio 0
	s_barrier
	ds_read_b128 v[80:83], v91 offset:16384
	ds_read_b128 v[94:97], v219 offset:16384
	ds_read_b128 v[98:101], v91 offset:18432
	ds_read_b128 v[102:105], v219 offset:18432
	ds_read_b128 v[106:109], v92 offset:16384
	ds_read_b128 v[110:113], v218 offset:16384
	ds_read_b128 v[114:117], v92 offset:18432
	ds_read_b128 v[118:121], v218 offset:18432
	ds_read_b128 v[122:125], v92 offset:20480
	ds_read_b128 v[126:129], v218 offset:20480
	ds_read_b128 v[130:133], v92 offset:22528
	ds_read_b128 v[134:137], v218 offset:22528
	s_add_i32 s55, s47, s36
	v_lshl_add_u64 v[84:85], s[58:59], 0, v[66:67]
	s_mov_b32 m0, s55
	s_nop 0
	global_load_lds_dwordx4 v[84:85], off
	v_lshl_add_u64 v[138:139], s[58:59], 0, v[70:71]
	s_add_i32 m0, s55, 0x2000
	s_nop 0
	global_load_lds_dwordx4 v[138:139], off
	v_lshl_add_u64 v[140:141], s[56:57], 0, v[64:65]
	s_mov_b32 m0, s25
	s_nop 0
	global_load_lds_dwordx4 v[140:141], off
	v_lshl_add_u64 v[142:143], s[56:57], 0, v[68:69]
	s_mov_b32 m0, s39
	s_nop 0
	global_load_lds_dwordx4 v[142:143], off
	s_waitcnt vmcnt(8)
	s_waitcnt lgkmcnt(0)
	s_barrier
; #define PG8_STAGE(bufoff, gbase, voff) do { _Pragma("unroll") for (int _i = 0; _i < 2; ++_i) \
;         __builtin_amdgcn_global_load_lds((const unsigned*)((const char*)(gbase) + (voff)[_i]), (LAS unsigned*)(lds + (bufoff) + ldsw + _i * 8192), 16, 0, 0); } while (0)
; #define PG8_LDA(dst, b, h) do { _Pragma("unroll") for (int m = 0; m < 4; ++m) _Pragma("unroll") for (int k = 0; k < 2; ++k) dst[m][k] = *(const LAS bf16x8*)(lds + PG8_SA(b, h) + aoff + m * 2048 + k * 1024); } while (0)
; #define PG8_LDB(dst, b, h) do { _Pragma("unroll") for (int n = 0; n < 2; ++n) _Pragma("unroll") for (int k = 0; k < 2; ++k) dst[n][k] = *(const LAS bf16x8*)(lds + PG8_SB(b, h) + boff + n * 2048 + k * 1024); } while (0)
; #define PG8_WAIT_V(n) asm volatile("s_waitcnt vmcnt(" #n ")" ::: "memory")
; #define PG8_WAIT_L(n) asm volatile("s_waitcnt lgkmcnt(" #n ")" ::: "memory")
; template <class Epi, class Sched>
; __device__ __forceinline__ void gemm_phase(LAS unsigned char* lds, const Gemm g, const Sched& S, const Epi& E) {
;     ...
;             PG8_LDB(B0, 0, 0); PG8_SCHED; PG8_LDA(At, 0, 0); PG8_STAGE(PG8_SA(1, 1), a1 + hstepA, voffA);
;             PG8_WAIT_L(8); PG8_BAR; PG8_WAIT_L(0); PG8_MMA(0, 0, At, B0); PG8_BAR; PG8_SCHED;
;             PG8_LDB(B1, 0, 1); PG8_STAGE(PG8_SB(0, 0), b2, voffB);
;             PG8_BAR; PG8_WAIT_L(0); if constexpr (!Epi::DIAG) PG8_MMA(0, 1, At, B1); PG8_BAR;
;             PG8_LDA(At, 0, 1); PG8_STAGE(PG8_SA(0, 0), a2, voffA);
;             PG8_BAR; PG8_WAIT_L(0); if constexpr (!Epi::DIAG) PG8_MMA(1, 0, At, B0); PG8_BAR; PG8_SCHED;
;             PG8_STAGE(PG8_SB(0, 1), b2 + hstepB, voffB);
;             PG8_WAIT_V(6); PG8_BAR; PG8_MMA(1, 1, At, B1); PG8_BAR;
;             PG8_LDB(B0, 1, 0); PG8_SCHED; PG8_LDA(At, 1, 0); PG8_STAGE(PG8_SA(0, 1), a2 + hstepA, voffA);
;             PG8_WAIT_L(8); PG8_BAR; PG8_WAIT_L(0); PG8_MMA(0, 0, At, B0); PG8_BAR; PG8_SCHED;
;             PG8_LDB(B1, 1, 1); PG8_STAGE(PG8_SB(1, 0), b3, voffB);
;             PG8_BAR; PG8_WAIT_L(0); if constexpr (!Epi::DIAG) PG8_MMA(0, 1, At, B1); PG8_BAR;
;             PG8_LDA(At, 1, 1); PG8_STAGE(PG8_SA(1, 0), a3, voffA);
;             PG8_BAR; PG8_WAIT_L(0); if constexpr (!Epi::DIAG) PG8_MMA(1, 0, At, B0); PG8_BAR; PG8_SCHED;
;             PG8_STAGE(PG8_SB(1, 1), b3 + hstepB, voffB);
;             PG8_WAIT_V(6); PG8_BAR; PG8_MMA(1, 1, At, B1); PG8_BAR;
	s_setprio 1
	v_mfma_f32_16x16x32_bf16 v[52:55], v[80:83], v[106:109], v[52:55]
	v_mfma_f32_16x16x32_bf16 v[48:51], v[98:101], v[106:109], v[48:51]
	v_mfma_f32_16x16x32_bf16 v[36:39], v[80:83], v[114:117], v[36:39]
	v_mfma_f32_16x16x32_bf16 v[32:35], v[98:101], v[114:117], v[32:35]
	v_mfma_f32_16x16x32_bf16 v[24:27], v[80:83], v[122:125], v[24:27]
	v_mfma_f32_16x16x32_bf16 v[16:19], v[98:101], v[122:125], v[16:19]
	v_mfma_f32_16x16x32_bf16 v[8:11], v[80:83], v[130:133], v[8:11]
	v_mfma_f32_16x16x32_bf16 v[0:3], v[98:101], v[130:133], v[0:3]
	v_mfma_f32_16x16x32_bf16 v[52:55], v[94:97], v[110:113], v[52:55]
	v_mfma_f32_16x16x32_bf16 v[48:51], v[102:105], v[110:113], v[48:51]
	v_mfma_f32_16x16x32_bf16 v[36:39], v[94:97], v[118:121], v[36:39]
	v_mfma_f32_16x16x32_bf16 v[32:35], v[102:105], v[118:121], v[32:35]
	v_mfma_f32_16x16x32_bf16 v[24:27], v[94:97], v[126:129], v[24:27]
	v_mfma_f32_16x16x32_bf16 v[16:19], v[102:105], v[126:129], v[16:19]
	v_mfma_f32_16x16x32_bf16 v[8:11], v[94:97], v[134:137], v[8:11]
	v_mfma_f32_16x16x32_bf16 v[0:3], v[102:105], v[134:137], v[0:3]
	s_setprio 0
	s_barrier
	ds_read_b128 v[80:83], v91 offset:32768
	ds_read_b128 v[94:97], v219 offset:32768
	ds_read_b128 v[98:101], v91 offset:34816
	ds_read_b128 v[102:105], v219 offset:34816
	ds_read_b128 v[106:109], v92 offset:32768
	ds_read_b128 v[110:113], v218 offset:32768
	ds_read_b128 v[114:117], v92 offset:34816
	ds_read_b128 v[118:121], v218 offset:34816
	ds_read_b128 v[122:125], v92 offset:36864
	ds_read_b128 v[126:129], v218 offset:36864
	ds_read_b128 v[130:133], v92 offset:38912
	ds_read_b128 v[134:137], v218 offset:38912
	s_add_i32 s55, s48, s36
	v_lshl_add_u64 v[144:145], v[84:85], 0, s[4:5]
	s_mov_b32 m0, s55
	s_nop 0
	global_load_lds_dwordx4 v[144:145], off
	v_lshl_add_u64 v[144:145], v[138:139], 0, s[4:5]
	s_add_i32 m0, s55, 0x2000
	s_nop 0
	global_load_lds_dwordx4 v[144:145], off
	v_lshl_add_u64 v[144:145], v[140:141], 0, s[4:5]
	s_mov_b32 m0, s40
	s_nop 0
	global_load_lds_dwordx4 v[144:145], off
	v_lshl_add_u64 v[144:145], v[142:143], 0, s[4:5]
	s_mov_b32 m0, s41
	s_nop 0
	global_load_lds_dwordx4 v[144:145], off
	s_waitcnt vmcnt(8)
	s_waitcnt lgkmcnt(0)
	s_barrier
	s_setprio 1
	v_mfma_f32_16x16x32_bf16 v[60:63], v[80:83], v[106:109], v[60:63]
	v_mfma_f32_16x16x32_bf16 v[56:59], v[98:101], v[106:109], v[56:59]
	v_mfma_f32_16x16x32_bf16 v[44:47], v[80:83], v[114:117], v[44:47]
	v_mfma_f32_16x16x32_bf16 v[40:43], v[98:101], v[114:117], v[40:43]
	v_mfma_f32_16x16x32_bf16 v[28:31], v[80:83], v[122:125], v[28:31]
	v_mfma_f32_16x16x32_bf16 v[20:23], v[98:101], v[122:125], v[20:23]
	v_mfma_f32_16x16x32_bf16 v[12:15], v[80:83], v[130:133], v[12:15]
	v_mfma_f32_16x16x32_bf16 v[4:7], v[98:101], v[130:133], v[4:7]
	v_mfma_f32_16x16x32_bf16 v[60:63], v[94:97], v[110:113], v[60:63]
	v_mfma_f32_16x16x32_bf16 v[56:59], v[102:105], v[110:113], v[56:59]
	v_mfma_f32_16x16x32_bf16 v[44:47], v[94:97], v[118:121], v[44:47]
	v_mfma_f32_16x16x32_bf16 v[40:43], v[102:105], v[118:121], v[40:43]
	v_mfma_f32_16x16x32_bf16 v[28:31], v[94:97], v[126:129], v[28:31]
	v_mfma_f32_16x16x32_bf16 v[20:23], v[102:105], v[126:129], v[20:23]
	v_mfma_f32_16x16x32_bf16 v[12:15], v[94:97], v[134:137], v[12:15]
	v_mfma_f32_16x16x32_bf16 v[4:7], v[102:105], v[134:137], v[4:7]
	s_setprio 0
	s_barrier
	ds_read_b128 v[80:83], v91 offset:49152
	ds_read_b128 v[94:97], v219 offset:49152
	ds_read_b128 v[98:101], v91 offset:51200
	ds_read_b128 v[102:105], v219 offset:51200
	ds_read_b128 v[106:109], v92 offset:49152
	ds_read_b128 v[110:113], v218 offset:49152
	ds_read_b128 v[114:117], v92 offset:51200
	ds_read_b128 v[118:121], v218 offset:51200
	ds_read_b128 v[122:125], v92 offset:53248
	ds_read_b128 v[126:129], v218 offset:53248
	ds_read_b128 v[130:133], v92 offset:55296
	ds_read_b128 v[134:137], v218 offset:55296
	s_add_i32 s55, s36, 0x18000
	v_lshl_add_u64 v[144:145], v[84:85], 0, s[12:13]
	s_mov_b32 m0, s55
	s_nop 0
	global_load_lds_dwordx4 v[144:145], off
	v_lshl_add_u64 v[144:145], v[138:139], 0, s[12:13]
	s_add_i32 m0, s55, 0x2000
	s_nop 0
	global_load_lds_dwordx4 v[144:145], off
	v_lshl_add_u64 v[144:145], v[140:141], 0, s[12:13]
	s_mov_b32 m0, s44
	s_nop 0
	global_load_lds_dwordx4 v[144:145], off
	v_lshl_add_u64 v[144:145], v[142:143], 0, s[12:13]
	s_mov_b32 m0, s45
	s_nop 0
	global_load_lds_dwordx4 v[144:145], off
	s_waitcnt vmcnt(8)
	s_waitcnt lgkmcnt(0)
	s_barrier
	s_setprio 1
	v_mfma_f32_16x16x32_bf16 v[52:55], v[80:83], v[106:109], v[52:55]
	v_mfma_f32_16x16x32_bf16 v[48:51], v[98:101], v[106:109], v[48:51]
	v_mfma_f32_16x16x32_bf16 v[36:39], v[80:83], v[114:117], v[36:39]
	v_mfma_f32_16x16x32_bf16 v[32:35], v[98:101], v[114:117], v[32:35]
	v_mfma_f32_16x16x32_bf16 v[24:27], v[80:83], v[122:125], v[24:27]
	v_mfma_f32_16x16x32_bf16 v[16:19], v[98:101], v[122:125], v[16:19]
	v_mfma_f32_16x16x32_bf16 v[8:11], v[80:83], v[130:133], v[8:11]
	v_mfma_f32_16x16x32_bf16 v[0:3], v[98:101], v[130:133], v[0:3]
	v_mfma_f32_16x16x32_bf16 v[52:55], v[94:97], v[110:113], v[52:55]
	v_mfma_f32_16x16x32_bf16 v[48:51], v[102:105], v[110:113], v[48:51]
	v_mfma_f32_16x16x32_bf16 v[36:39], v[94:97], v[118:121], v[36:39]
	v_mfma_f32_16x16x32_bf16 v[32:35], v[102:105], v[118:121], v[32:35]
	v_mfma_f32_16x16x32_bf16 v[24:27], v[94:97], v[126:129], v[24:27]
	v_mfma_f32_16x16x32_bf16 v[16:19], v[102:105], v[126:129], v[16:19]
	v_mfma_f32_16x16x32_bf16 v[8:11], v[94:97], v[134:137], v[8:11]
	v_mfma_f32_16x16x32_bf16 v[0:3], v[102:105], v[134:137], v[0:3]
	s_setprio 0
	s_add_i32 s54, s54, 2
	s_add_u32 s62, s62, 0x100
	s_and_b32 s62, s62, 0x7ff
	s_cmp_gt_u32 s54, 13
	s_barrier
	s_cbranch_scc0 .LBB0_1385
; __device__ __forceinline__ u32x4 pack8(const float* f) { u32x4 w; w.x = pk2(f[0], f[1]); w.y = pk2(f[2], f[3]); w.z = pk2(f[4], f[5]); w.w = pk2(f[6], f[7]); return w; }
;     __device__ __forceinline__ void operator()(const Acc& acc, const Unit& u, int wr, int wc, int fr, int fq) const { if (u.piece == 0) e1(acc, u, wr, wc, fr, fq); else e2(acc, u, wr, wc, fr, fq); }
; template <class Epi, class Sched>
; __device__ __forceinline__ void gemm_phase(LAS unsigned char* lds, const Gemm g, const Sched& S, const Epi& E) {
;     ...
;         cur = nxt; cA = nA; cB = nB; ++ui;
;     __device__ __forceinline__ void operator()(const Acc& acc, const Unit& u, int wr, int wc, int fr, int fq) const {
;         const int row0 = u.pm * HALF + wr * 64 + fr, col0 = u.pn * HALF + wc * 32 + 8 * fq;
; #pragma unroll
;         for (int m = 0; m < 4; ++m) { const size_t row = (size_t)(row0 + m * 16); const bf16_t* pr = proj + row * NPROJ + col0;
;             float ga[8], gb[8], v[8]; unpack8(*(const u32x4*)(pr + C_GA), ga); unpack8(*(const u32x4*)(pr + C_GB), gb);
; #pragma unroll
;             for (int n = 0; n < 2; ++n) {
;                 const f32x4 A4 = {ga[4 * n], ga[4 * n + 1], ga[4 * n + 2], ga[4 * n + 3]}, B4 = {gb[4 * n], gb[4 * n + 1], gb[4 * n + 2], gb[4 * n + 3]};
;                 const f32x4 aa = A4 * (-1.4426950408889634f), ab = B4 * (-1.4426950408889634f);
;                 f32x4 ta, tb;
; #pragma unroll
;                 for (int j = 0; j < 4; ++j) { ta[j] = __builtin_amdgcn_exp2f(aa[j]); tb[j] = __builtin_amdgcn_exp2f(ab[j]); }
;                 ta = ta + 1.0f; tb = tb + 1.0f;
; #pragma unroll
;                 for (int j = 0; j < 4; ++j) { ta[j] = __builtin_amdgcn_rcpf(ta[j]); tb[j] = __builtin_amdgcn_rcpf(tb[j]); }
;                 const f32x4 r = acc[0][0][m][n] * ta + acc[1][1][m][n] * tb;
; #pragma unroll
;                 for (int j = 0; j < 4; ++j) v[4 * n + j] = r[j]; }
;             *(u32x4*)(O + row * DM + col0) = pack8(v); }
	v_lshl_or_b32 v80, s51, 7, v90
	v_lshl_add_u32 v82, s24, 7, v88
	v_ashrrev_i32_e32 v81, 31, v80
	v_mov_b64_e32 v[84:85], s[10:11]
	v_mad_i64_i32 v[94:95], s[26:27], v82, s49, v[84:85]
	v_lshlrev_b64 v[80:81], 1, v[80:81]
	v_lshl_add_u64 v[98:99], v[94:95], 0, v[80:81]
	v_add_co_u32_e32 v94, vcc, 0x2000, v98
	v_ashrrev_i32_e32 v83, 31, v82
	s_nop 0
	v_addc_co_u32_e32 v95, vcc, 0, v99, vcc
	v_add_co_u32_e32 v98, vcc, s50, v98
	global_load_dwordx4 v[94:97], v[94:95], off offset:2048
	s_nop 0
	v_addc_co_u32_e32 v99, vcc, 0, v99, vcc
	global_load_dwordx4 v[98:101], v[98:99], off offset:2048
	v_or_b32_e32 v210, 16, v82
	v_mad_i64_i32 v[212:213], s[26:27], v210, s49, v[84:85]
	v_lshl_add_u64 v[212:213], v[212:213], 0, v[80:81]
	v_add_co_u32_e32 v214, vcc, s42, v212
	s_nop 1
	v_addc_co_u32_e32 v215, vcc, 0, v213, vcc
	v_add_co_u32_e32 v212, vcc, s50, v212
	s_nop 1
	v_addc_co_u32_e32 v213, vcc, 0, v213, vcc
	global_load_dwordx4 v[186:189], v[214:215], off offset:2048
	global_load_dwordx4 v[190:193], v[212:213], off offset:2048
	v_or_b32_e32 v210, 32, v82
	v_mad_i64_i32 v[212:213], s[26:27], v210, s49, v[84:85]
	v_lshl_add_u64 v[212:213], v[212:213], 0, v[80:81]
	v_add_co_u32_e32 v214, vcc, s42, v212
	s_nop 1
	v_addc_co_u32_e32 v215, vcc, 0, v213, vcc
	v_add_co_u32_e32 v212, vcc, s50, v212
	s_nop 1
	v_addc_co_u32_e32 v213, vcc, 0, v213, vcc
	global_load_dwordx4 v[194:197], v[214:215], off offset:2048
	global_load_dwordx4 v[198:201], v[212:213], off offset:2048
	v_or_b32_e32 v210, 48, v82
	v_mad_i64_i32 v[212:213], s[26:27], v210, s49, v[84:85]
	v_lshl_add_u64 v[212:213], v[212:213], 0, v[80:81]
	v_add_co_u32_e32 v214, vcc, s42, v212
	s_nop 1
	v_addc_co_u32_e32 v215, vcc, 0, v213, vcc
	v_add_co_u32_e32 v212, vcc, s50, v212
	s_nop 1
	v_addc_co_u32_e32 v213, vcc, 0, v213, vcc
	global_load_dwordx4 v[202:205], v[214:215], off offset:2048
	global_load_dwordx4 v[206:209], v[212:213], off offset:2048
	s_mov_b32 s51, s16
	s_mov_b32 s24, s18
	s_mov_b64 s[28:29], s[22:23]
	s_waitcnt vmcnt(6)
	v_lshlrev_b32_e32 v102, 16, v94
	v_and_b32_e32 v94, 0xffff0000, v94
	v_lshlrev_b32_e32 v103, 16, v95
	v_and_b32_e32 v95, 0xffff0000, v95
	v_lshlrev_b32_e32 v104, 16, v96
	v_and_b32_e32 v96, 0xffff0000, v96
	v_lshlrev_b32_e32 v106, 16, v98
	v_and_b32_e32 v98, 0xffff0000, v98
	v_lshlrev_b32_e32 v105, 16, v97
	v_and_b32_e32 v97, 0xffff0000, v97
	v_lshlrev_b32_e32 v107, 16, v99
	v_and_b32_e32 v99, 0xffff0000, v99
	v_lshlrev_b32_e32 v108, 16, v100
	v_and_b32_e32 v100, 0xffff0000, v100
	v_lshlrev_b32_e32 v109, 16, v101
	v_and_b32_e32 v110, 0xffff0000, v101
	v_mul_f32_e32 v101, 0xbfb8aa3b, v102
	v_mul_f32_e32 v102, 0xbfb8aa3b, v94
	v_mul_f32_e32 v103, 0xbfb8aa3b, v103
	v_mul_f32_e32 v111, 0xbfb8aa3b, v95
	v_mul_f32_e32 v112, 0xbfb8aa3b, v96
	v_mul_f32_e32 v106, 0xbfb8aa3b, v106
	v_mul_f32_e32 v114, 0xbfb8aa3b, v98
	v_mul_f32_e32 v104, 0xbfb8aa3b, v104
	v_mul_f32_e32 v113, 0xbfb8aa3b, v97
	v_exp_f32_e32 v95, v102
	v_exp_f32_e32 v96, v103
	v_mul_f32_e32 v107, 0xbfb8aa3b, v107
	v_exp_f32_e32 v97, v111
	v_mul_f32_e32 v111, 0xbfb8aa3b, v99
	v_mul_f32_e32 v108, 0xbfb8aa3b, v108
	v_exp_f32_e32 v99, v112
	v_mul_f32_e32 v112, 0xbfb8aa3b, v100
	v_exp_f32_e32 v102, v106
	v_exp_f32_e32 v103, v114
	v_mul_f32_e32 v105, 0xbfb8aa3b, v105
	v_exp_f32_e32 v94, v101
	v_exp_f32_e32 v98, v104
	v_mul_f32_e32 v109, 0xbfb8aa3b, v109
	v_mul_f32_e32 v110, 0xbfb8aa3b, v110
	v_exp_f32_e32 v104, v107
	v_exp_f32_e32 v106, v108
	v_exp_f32_e32 v107, v112
	v_exp_f32_e32 v100, v105
	v_exp_f32_e32 v105, v111
	v_exp_f32_e32 v108, v109
	v_exp_f32_e32 v109, v110
	v_exp_f32_e32 v101, v113
	v_pk_add_f32 v[102:103], v[102:103], 1.0 op_sel_hi:[1,0]
	v_pk_add_f32 v[94:95], v[94:95], 1.0 op_sel_hi:[1,0]
	v_pk_add_f32 v[106:107], v[106:107], 1.0 op_sel_hi:[1,0]
	v_rcp_f32_e32 v102, v102
	v_rcp_f32_e32 v103, v103
	v_pk_add_f32 v[98:99], v[98:99], 1.0 op_sel_hi:[1,0]
	v_pk_add_f32 v[104:105], v[104:105], 1.0 op_sel_hi:[1,0]
	v_rcp_f32_e32 v94, v94
	v_rcp_f32_e32 v95, v95
	v_pk_add_f32 v[108:109], v[108:109], 1.0 op_sel_hi:[1,0]
	v_rcp_f32_e32 v106, v106
	v_rcp_f32_e32 v107, v107
	v_pk_add_f32 v[96:97], v[96:97], 1.0 op_sel_hi:[1,0]
	v_pk_add_f32 v[100:101], v[100:101], 1.0 op_sel_hi:[1,0]
	v_rcp_f32_e32 v98, v98
	v_rcp_f32_e32 v99, v99
	v_rcp_f32_e32 v104, v104
	v_rcp_f32_e32 v105, v105
	v_rcp_f32_e32 v108, v108
	v_rcp_f32_e32 v109, v109
	v_rcp_f32_e32 v96, v96
	v_rcp_f32_e32 v97, v97
	v_rcp_f32_e32 v100, v100
	v_rcp_f32_e32 v101, v101
	v_pk_mul_f32 v[52:53], v[52:53], v[102:103]
	v_pk_mul_f32 v[48:49], v[48:49], v[106:107]
	v_pk_fma_f32 v[52:53], v[60:61], v[94:95], v[52:53]
	v_pk_mul_f32 v[54:55], v[54:55], v[104:105]
	v_pk_mul_f32 v[50:51], v[50:51], v[108:109]
	v_pk_fma_f32 v[56:57], v[56:57], v[98:99], v[48:49]
	v_cvt_pk_bf16_f32 v48, v52, v53
	v_lshlrev_b64 v[52:53], 12, v[82:83]
	v_pk_fma_f32 v[54:55], v[62:63], v[96:97], v[54:55]
	v_pk_fma_f32 v[58:59], v[58:59], v[100:101], v[50:51]
	v_lshl_add_u64 v[52:53], s[8:9], 0, v[52:53]
	v_cvt_pk_bf16_f32 v49, v54, v55
	v_cvt_pk_bf16_f32 v50, v56, v57
	v_cvt_pk_bf16_f32 v51, v58, v59
	v_lshl_add_u64 v[52:53], v[52:53], 0, v[80:81]
	v_or_b32_e32 v56, 16, v82
	global_store_dwordx4 v[52:53], v[48:51], off
	v_ashrrev_i32_e32 v57, 31, v56
	s_nop 0
	v_mad_i64_i32 v[48:49], s[26:27], v56, s49, v[84:85]
	v_lshl_add_u64 v[52:53], v[48:49], 0, v[80:81]
	v_add_co_u32_e32 v48, vcc, s42, v52
	s_nop 1
	v_addc_co_u32_e32 v49, vcc, 0, v53, vcc
	v_add_co_u32_e32 v52, vcc, s50, v52
	s_waitcnt vmcnt(5)
; __device__ __forceinline__ u32x4 pack8(const float* f) { u32x4 w; w.x = pk2(f[0], f[1]); w.y = pk2(f[2], f[3]); w.z = pk2(f[4], f[5]); w.w = pk2(f[6], f[7]); return w; }
;     __device__ __forceinline__ void operator()(const Acc& acc, const Unit& u, int wr, int wc, int fr, int fq) const {
;     ...
;         for (int m = 0; m < 4; ++m) { const size_t row = (size_t)(row0 + m * 16); const bf16_t* pr = proj + row * NPROJ + col0;
;             float ga[8], gb[8], v[8]; unpack8(*(const u32x4*)(pr + C_GA), ga); unpack8(*(const u32x4*)(pr + C_GB), gb);
; #pragma unroll
;             for (int n = 0; n < 2; ++n) {
;                 const f32x4 A4 = {ga[4 * n], ga[4 * n + 1], ga[4 * n + 2], ga[4 * n + 3]}, B4 = {gb[4 * n], gb[4 * n + 1], gb[4 * n + 2], gb[4 * n + 3]};
;                 const f32x4 aa = A4 * (-1.4426950408889634f), ab = B4 * (-1.4426950408889634f);
;                 f32x4 ta, tb;
; #pragma unroll
;                 for (int j = 0; j < 4; ++j) { ta[j] = __builtin_amdgcn_exp2f(aa[j]); tb[j] = __builtin_amdgcn_exp2f(ab[j]); }
;                 ta = ta + 1.0f; tb = tb + 1.0f;
; #pragma unroll
;                 for (int j = 0; j < 4; ++j) { ta[j] = __builtin_amdgcn_rcpf(ta[j]); tb[j] = __builtin_amdgcn_rcpf(tb[j]); }
;                 const f32x4 r = acc[0][0][m][n] * ta + acc[1][1][m][n] * tb;
; #pragma unroll
;                 for (int j = 0; j < 4; ++j) v[4 * n + j] = r[j]; }
;             *(u32x4*)(O + row * DM + col0) = pack8(v); }
	v_mov_b32_e32 v48, v186
	v_mov_b32_e32 v49, v187
	v_mov_b32_e32 v50, v188
	v_mov_b32_e32 v51, v189
	s_nop 0
	v_addc_co_u32_e32 v53, vcc, 0, v53, vcc
	v_mov_b32_e32 v52, v190
	v_mov_b32_e32 v53, v191
	v_mov_b32_e32 v54, v192
	v_mov_b32_e32 v55, v193
	v_lshlrev_b32_e32 v59, 16, v49
	v_and_b32_e32 v49, 0xffff0000, v49
	v_lshlrev_b32_e32 v58, 16, v48
	v_lshlrev_b32_e32 v63, 16, v53
	v_and_b32_e32 v53, 0xffff0000, v53
	v_lshlrev_b32_e32 v62, 16, v52
	v_and_b32_e32 v52, 0xffff0000, v52
	v_lshlrev_b32_e32 v83, 16, v54
	v_and_b32_e32 v54, 0xffff0000, v54
	v_lshlrev_b32_e32 v94, 16, v55
	v_and_b32_e32 v55, 0xffff0000, v55
	v_mul_f32_e32 v63, 0xbfb8aa3b, v63
	v_mul_f32_e32 v97, 0xbfb8aa3b, v53
	v_and_b32_e32 v48, 0xffff0000, v48
	v_lshlrev_b32_e32 v60, 16, v50
	v_and_b32_e32 v50, 0xffff0000, v50
	v_lshlrev_b32_e32 v61, 16, v51
	v_and_b32_e32 v51, 0xffff0000, v51
	v_mul_f32_e32 v62, 0xbfb8aa3b, v62
	v_mul_f32_e32 v52, 0xbfb8aa3b, v52
	v_mul_f32_e32 v59, 0xbfb8aa3b, v59
	v_mul_f32_e32 v96, 0xbfb8aa3b, v49
	v_mul_f32_e32 v99, 0xbfb8aa3b, v54
	v_mul_f32_e32 v102, 0xbfb8aa3b, v55
	v_exp_f32_e32 v54, v63
	v_exp_f32_e32 v55, v97
	v_mul_f32_e32 v58, 0xbfb8aa3b, v58
	v_mul_f32_e32 v95, 0xbfb8aa3b, v48
	v_mul_f32_e32 v98, 0xbfb8aa3b, v50
	v_mul_f32_e32 v101, 0xbfb8aa3b, v51
	v_exp_f32_e32 v50, v62
	v_exp_f32_e32 v51, v52
	v_exp_f32_e32 v52, v59
	v_exp_f32_e32 v53, v96
	v_exp_f32_e32 v48, v58
	v_exp_f32_e32 v49, v95
	v_mul_f32_e32 v60, 0xbfb8aa3b, v60
	v_mul_f32_e32 v83, 0xbfb8aa3b, v83
	v_mul_f32_e32 v100, 0xbfb8aa3b, v61
	v_mul_f32_e32 v94, 0xbfb8aa3b, v94
	v_exp_f32_e32 v58, v60
	v_exp_f32_e32 v60, v83
	v_exp_f32_e32 v61, v99
	v_pk_add_f32 v[54:55], v[54:55], 1.0 op_sel_hi:[1,0]
	v_exp_f32_e32 v59, v98
	v_exp_f32_e32 v94, v94
	v_exp_f32_e32 v95, v102
	v_pk_add_f32 v[52:53], v[52:53], 1.0 op_sel_hi:[1,0]
	v_pk_add_f32 v[50:51], v[50:51], 1.0 op_sel_hi:[1,0]
	v_rcp_f32_e32 v54, v54
	v_rcp_f32_e32 v55, v55
	v_exp_f32_e32 v62, v100
	v_exp_f32_e32 v63, v101
	v_pk_add_f32 v[48:49], v[48:49], 1.0 op_sel_hi:[1,0]
	v_rcp_f32_e32 v50, v50
	v_rcp_f32_e32 v51, v51
	v_rcp_f32_e32 v52, v52
	v_rcp_f32_e32 v53, v53
	v_rcp_f32_e32 v48, v48
	v_rcp_f32_e32 v49, v49
	v_pk_add_f32 v[60:61], v[60:61], 1.0 op_sel_hi:[1,0]
	v_pk_add_f32 v[58:59], v[58:59], 1.0 op_sel_hi:[1,0]
	v_pk_add_f32 v[94:95], v[94:95], 1.0 op_sel_hi:[1,0]
	v_rcp_f32_e32 v60, v60
	v_pk_mul_f32 v[38:39], v[38:39], v[54:55]
	v_rcp_f32_e32 v61, v61
	v_pk_add_f32 v[62:63], v[62:63], 1.0 op_sel_hi:[1,0]
	v_rcp_f32_e32 v58, v58
	v_rcp_f32_e32 v59, v59
	v_pk_mul_f32 v[36:37], v[36:37], v[50:51]
	v_pk_fma_f32 v[38:39], v[46:47], v[52:53], v[38:39]
	v_rcp_f32_e32 v46, v94
	v_rcp_f32_e32 v47, v95
	v_pk_fma_f32 v[36:37], v[44:45], v[48:49], v[36:37]
	v_rcp_f32_e32 v44, v62
	v_rcp_f32_e32 v45, v63
	v_pk_mul_f32 v[32:33], v[32:33], v[60:61]
	s_nop 0
	v_pk_fma_f32 v[40:41], v[40:41], v[58:59], v[32:33]
	v_pk_mul_f32 v[32:33], v[34:35], v[46:47]
	v_cvt_pk_bf16_f32 v34, v40, v41
	v_pk_fma_f32 v[42:43], v[42:43], v[44:45], v[32:33]
	v_cvt_pk_bf16_f32 v32, v36, v37
	v_lshlrev_b64 v[36:37], 12, v[56:57]
	v_lshl_add_u64 v[36:37], s[8:9], 0, v[36:37]
	v_cvt_pk_bf16_f32 v33, v38, v39
	v_cvt_pk_bf16_f32 v35, v42, v43
	v_lshl_add_u64 v[36:37], v[36:37], 0, v[80:81]
	v_or_b32_e32 v40, 32, v82
	global_store_dwordx4 v[36:37], v[32:35], off
	v_ashrrev_i32_e32 v41, 31, v40
	s_nop 0
	v_mad_i64_i32 v[32:33], s[26:27], v40, s49, v[84:85]
	v_lshl_add_u64 v[36:37], v[32:33], 0, v[80:81]
	v_add_co_u32_e32 v32, vcc, s42, v36
	s_nop 1
	v_addc_co_u32_e32 v33, vcc, 0, v37, vcc
	v_add_co_u32_e32 v36, vcc, s50, v36
	s_waitcnt vmcnt(4)
; __device__ __forceinline__ u32x4 pack8(const float* f) { u32x4 w; w.x = pk2(f[0], f[1]); w.y = pk2(f[2], f[3]); w.z = pk2(f[4], f[5]); w.w = pk2(f[6], f[7]); return w; }
; #define PG8_WAIT_V(n) asm volatile("s_waitcnt vmcnt(" #n ")" ::: "memory")
; #define PG8_BAR __builtin_amdgcn_s_barrier()
; template <class Epi, class Sched>
; __device__ __forceinline__ void gemm_phase(LAS unsigned char* lds, const Gemm g, const Sched& S, const Epi& E) {
;     ...
;         if (!has_next) break;
; #pragma unroll
;         for (int a = 0; a < 2; ++a)
; #pragma unroll
;             for (int b = 0; b < 2; ++b)
; #pragma unroll
;                 for (int m = 0; m < 4; ++m)
; #pragma unroll
;                     for (int n = 0; n < 2; ++n) acc[a][b][m][n] = (f32x4){0.f, 0.f, 0.f, 0.f};
;         cur = nxt; cA = nA; cB = nB; ++ui;
;     }
;     PG8_WAIT_V(0);
;     if (wr == 0) PG8_BAR;
;     PG8_BAR;
;     __device__ __forceinline__ void operator()(const Acc& acc, const Unit& u, int wr, int wc, int fr, int fq) const {
;     ...
;         for (int m = 0; m < 4; ++m) { const size_t row = (size_t)(row0 + m * 16); const bf16_t* pr = proj + row * NPROJ + col0;
;             float ga[8], gb[8], v[8]; unpack8(*(const u32x4*)(pr + C_GA), ga); unpack8(*(const u32x4*)(pr + C_GB), gb);
; #pragma unroll
;             for (int n = 0; n < 2; ++n) {
;                 const f32x4 A4 = {ga[4 * n], ga[4 * n + 1], ga[4 * n + 2], ga[4 * n + 3]}, B4 = {gb[4 * n], gb[4 * n + 1], gb[4 * n + 2], gb[4 * n + 3]};
;                 const f32x4 aa = A4 * (-1.4426950408889634f), ab = B4 * (-1.4426950408889634f);
;                 f32x4 ta, tb;
; #pragma unroll
;                 for (int j = 0; j < 4; ++j) { ta[j] = __builtin_amdgcn_exp2f(aa[j]); tb[j] = __builtin_amdgcn_exp2f(ab[j]); }
;                 ta = ta + 1.0f; tb = tb + 1.0f;
; #pragma unroll
;                 for (int j = 0; j < 4; ++j) { ta[j] = __builtin_amdgcn_rcpf(ta[j]); tb[j] = __builtin_amdgcn_rcpf(tb[j]); }
;                 const f32x4 r = acc[0][0][m][n] * ta + acc[1][1][m][n] * tb;
; #pragma unroll
;                 for (int j = 0; j < 4; ++j) v[4 * n + j] = r[j]; }
;             *(u32x4*)(O + row * DM + col0) = pack8(v); }
	v_mov_b32_e32 v32, v194
	v_mov_b32_e32 v33, v195
	v_mov_b32_e32 v34, v196
	v_mov_b32_e32 v35, v197
	s_nop 0
	v_addc_co_u32_e32 v37, vcc, 0, v37, vcc
	v_mov_b32_e32 v36, v198
	v_mov_b32_e32 v37, v199
	v_mov_b32_e32 v38, v200
	v_mov_b32_e32 v39, v201
	v_lshlrev_b32_e32 v43, 16, v33
	v_and_b32_e32 v33, 0xffff0000, v33
	v_lshlrev_b32_e32 v44, 16, v34
	v_lshlrev_b32_e32 v46, 16, v36
	v_and_b32_e32 v36, 0xffff0000, v36
	v_lshlrev_b32_e32 v47, 16, v37
	v_and_b32_e32 v37, 0xffff0000, v37
	v_and_b32_e32 v34, 0xffff0000, v34
	v_lshlrev_b32_e32 v45, 16, v35
	v_and_b32_e32 v35, 0xffff0000, v35
	v_lshlrev_b32_e32 v48, 16, v38
	v_and_b32_e32 v38, 0xffff0000, v38
	v_lshlrev_b32_e32 v49, 16, v39
	v_and_b32_e32 v39, 0xffff0000, v39
	v_mul_f32_e32 v46, 0xbfb8aa3b, v46
	v_mul_f32_e32 v36, 0xbfb8aa3b, v36
	v_mul_f32_e32 v47, 0xbfb8aa3b, v47
	v_mul_f32_e32 v52, 0xbfb8aa3b, v37
	v_lshlrev_b32_e32 v42, 16, v32
	v_and_b32_e32 v32, 0xffff0000, v32
	v_mul_f32_e32 v43, 0xbfb8aa3b, v43
	v_mul_f32_e32 v51, 0xbfb8aa3b, v33
	v_mul_f32_e32 v53, 0xbfb8aa3b, v34
	v_mul_f32_e32 v54, 0xbfb8aa3b, v38
	v_mul_f32_e32 v55, 0xbfb8aa3b, v35
	v_mul_f32_e32 v56, 0xbfb8aa3b, v39
	v_exp_f32_e32 v34, v46
	v_exp_f32_e32 v35, v36
	v_exp_f32_e32 v38, v47
	v_exp_f32_e32 v39, v52
	v_mul_f32_e32 v42, 0xbfb8aa3b, v42
	v_mul_f32_e32 v50, 0xbfb8aa3b, v32
	v_exp_f32_e32 v36, v43
	v_exp_f32_e32 v37, v51
	v_exp_f32_e32 v32, v42
	v_exp_f32_e32 v33, v50
	v_mul_f32_e32 v44, 0xbfb8aa3b, v44
	v_mul_f32_e32 v48, 0xbfb8aa3b, v48
	v_mul_f32_e32 v45, 0xbfb8aa3b, v45
	v_pk_add_f32 v[38:39], v[38:39], 1.0 op_sel_hi:[1,0]
	v_pk_add_f32 v[34:35], v[34:35], 1.0 op_sel_hi:[1,0]
	v_exp_f32_e32 v42, v44
	v_exp_f32_e32 v44, v48
	v_exp_f32_e32 v46, v45
	v_pk_add_f32 v[36:37], v[36:37], 1.0 op_sel_hi:[1,0]
	v_rcp_f32_e32 v34, v34
	v_rcp_f32_e32 v35, v35
	v_rcp_f32_e32 v38, v38
	v_rcp_f32_e32 v39, v39
	v_exp_f32_e32 v45, v54
	v_mul_f32_e32 v49, 0xbfb8aa3b, v49
	v_exp_f32_e32 v43, v53
	v_pk_add_f32 v[32:33], v[32:33], 1.0 op_sel_hi:[1,0]
	v_rcp_f32_e32 v36, v36
	v_rcp_f32_e32 v37, v37
	v_exp_f32_e32 v48, v49
	v_exp_f32_e32 v49, v56
	v_rcp_f32_e32 v32, v32
	v_rcp_f32_e32 v33, v33
	v_exp_f32_e32 v47, v55
	v_pk_mul_f32 v[24:25], v[24:25], v[34:35]
	v_pk_mul_f32 v[26:27], v[26:27], v[38:39]
	v_pk_add_f32 v[34:35], v[44:45], 1.0 op_sel_hi:[1,0]
	v_pk_fma_f32 v[26:27], v[30:31], v[36:37], v[26:27]
	v_pk_add_f32 v[30:31], v[42:43], 1.0 op_sel_hi:[1,0]
	v_rcp_f32_e32 v34, v34
	v_rcp_f32_e32 v35, v35
	v_pk_fma_f32 v[24:25], v[28:29], v[32:33], v[24:25]
	v_pk_add_f32 v[32:33], v[48:49], 1.0 op_sel_hi:[1,0]
	v_rcp_f32_e32 v30, v30
	v_rcp_f32_e32 v31, v31
	v_pk_add_f32 v[28:29], v[46:47], 1.0 op_sel_hi:[1,0]
	v_rcp_f32_e32 v32, v32
	v_rcp_f32_e32 v33, v33
	v_rcp_f32_e32 v28, v28
	v_rcp_f32_e32 v29, v29
	v_pk_mul_f32 v[16:17], v[16:17], v[34:35]
	s_nop 0
	v_pk_fma_f32 v[20:21], v[20:21], v[30:31], v[16:17]
	v_pk_mul_f32 v[16:17], v[18:19], v[32:33]
	v_cvt_pk_bf16_f32 v18, v20, v21
	v_lshlrev_b64 v[20:21], 12, v[40:41]
	v_pk_fma_f32 v[22:23], v[22:23], v[28:29], v[16:17]
	v_lshl_add_u64 v[20:21], s[8:9], 0, v[20:21]
	v_cvt_pk_bf16_f32 v16, v24, v25
	v_cvt_pk_bf16_f32 v17, v26, v27
	v_cvt_pk_bf16_f32 v19, v22, v23
	v_lshl_add_u64 v[20:21], v[20:21], 0, v[80:81]
	v_or_b32_e32 v24, 48, v82
	global_store_dwordx4 v[20:21], v[16:19], off
	v_ashrrev_i32_e32 v25, 31, v24
	s_nop 0
	v_mad_i64_i32 v[16:17], s[26:27], v24, s49, v[84:85]
	v_lshl_add_u64 v[20:21], v[16:17], 0, v[80:81]
	v_add_co_u32_e32 v16, vcc, s42, v20
	s_mov_b64 s[26:27], s[20:21]
	s_nop 0
	v_addc_co_u32_e32 v17, vcc, 0, v21, vcc
	v_add_co_u32_e32 v20, vcc, s50, v20
	s_waitcnt vmcnt(3)
	v_mov_b32_e32 v16, v202
	v_mov_b32_e32 v17, v203
	v_mov_b32_e32 v18, v204
	v_mov_b32_e32 v19, v205
	s_nop 0
	v_addc_co_u32_e32 v21, vcc, 0, v21, vcc
	v_mov_b32_e32 v20, v206
	v_mov_b32_e32 v21, v207
	v_mov_b32_e32 v22, v208
	v_mov_b32_e32 v23, v209
	s_and_b64 vcc, exec, s[6:7]
	v_lshlrev_b32_e32 v29, 16, v19
	v_and_b32_e32 v30, 0xffff0000, v19
	v_lshlrev_b32_e32 v26, 16, v16
	v_lshlrev_b32_e32 v19, 16, v20
	v_and_b32_e32 v20, 0xffff0000, v20
	v_and_b32_e32 v16, 0xffff0000, v16
	v_lshlrev_b32_e32 v28, 16, v18
	v_and_b32_e32 v18, 0xffff0000, v18
	v_lshlrev_b32_e32 v31, 16, v21
	v_and_b32_e32 v21, 0xffff0000, v21
	v_mul_f32_e32 v19, 0xbfb8aa3b, v19
	v_mul_f32_e32 v20, 0xbfb8aa3b, v20
	v_lshlrev_b32_e32 v27, 16, v17
	v_and_b32_e32 v17, 0xffff0000, v17
	v_lshlrev_b32_e32 v32, 16, v22
	v_and_b32_e32 v22, 0xffff0000, v22
	v_lshlrev_b32_e32 v33, 16, v23
	v_and_b32_e32 v34, 0xffff0000, v23
	v_mul_f32_e32 v23, 0xbfb8aa3b, v26
	v_mul_f32_e32 v26, 0xbfb8aa3b, v16
	v_mul_f32_e32 v31, 0xbfb8aa3b, v31
	v_mul_f32_e32 v36, 0xbfb8aa3b, v21
	v_mul_f32_e32 v37, 0xbfb8aa3b, v18
	v_exp_f32_e32 v18, v19
	v_exp_f32_e32 v19, v20
	v_mul_f32_e32 v27, 0xbfb8aa3b, v27
	v_mul_f32_e32 v35, 0xbfb8aa3b, v17
	v_mul_f32_e32 v38, 0xbfb8aa3b, v22
	v_exp_f32_e32 v16, v23
	v_exp_f32_e32 v17, v26
	v_exp_f32_e32 v22, v31
	v_exp_f32_e32 v23, v36
	v_exp_f32_e32 v20, v27
	v_exp_f32_e32 v21, v35
	v_pk_add_f32 v[18:19], v[18:19], 1.0 op_sel_hi:[1,0]
	v_pk_add_f32 v[16:17], v[16:17], 1.0 op_sel_hi:[1,0]
	v_pk_add_f32 v[22:23], v[22:23], 1.0 op_sel_hi:[1,0]
	v_rcp_f32_e32 v18, v18
	v_rcp_f32_e32 v19, v19
	v_pk_add_f32 v[20:21], v[20:21], 1.0 op_sel_hi:[1,0]
	v_rcp_f32_e32 v16, v16
	v_rcp_f32_e32 v17, v17
	v_rcp_f32_e32 v22, v22
	v_rcp_f32_e32 v23, v23
	v_rcp_f32_e32 v20, v20
	v_rcp_f32_e32 v21, v21
	v_mul_f32_e32 v28, 0xbfb8aa3b, v28
	v_mul_f32_e32 v32, 0xbfb8aa3b, v32
	v_pk_mul_f32 v[8:9], v[8:9], v[18:19]
	v_exp_f32_e32 v26, v28
	v_exp_f32_e32 v28, v32
	v_pk_mul_f32 v[10:11], v[10:11], v[22:23]
	v_pk_fma_f32 v[8:9], v[12:13], v[16:17], v[8:9]
	v_mul_f32_e32 v12, 0xbfb8aa3b, v29
	v_exp_f32_e32 v29, v38
	v_exp_f32_e32 v27, v37
	v_pk_fma_f32 v[10:11], v[14:15], v[20:21], v[10:11]
	v_mul_f32_e32 v13, 0xbfb8aa3b, v33
	v_mul_f32_e32 v15, 0xbfb8aa3b, v34
	v_exp_f32_e32 v14, v13
	v_mul_f32_e32 v13, 0xbfb8aa3b, v30
	v_exp_f32_e32 v15, v15
	v_exp_f32_e32 v12, v12
	v_exp_f32_e32 v13, v13
	v_pk_add_f32 v[18:19], v[28:29], 1.0 op_sel_hi:[1,0]
	v_pk_add_f32 v[16:17], v[26:27], 1.0 op_sel_hi:[1,0]
	v_rcp_f32_e32 v18, v18
	v_rcp_f32_e32 v19, v19
	v_pk_add_f32 v[14:15], v[14:15], 1.0 op_sel_hi:[1,0]
	v_rcp_f32_e32 v16, v16
	v_rcp_f32_e32 v17, v17
	v_pk_add_f32 v[12:13], v[12:13], 1.0 op_sel_hi:[1,0]
	v_rcp_f32_e32 v14, v14
	v_rcp_f32_e32 v15, v15
	v_rcp_f32_e32 v12, v12
	v_rcp_f32_e32 v13, v13
	v_pk_mul_f32 v[0:1], v[0:1], v[18:19]
	s_nop 0
	v_pk_fma_f32 v[4:5], v[4:5], v[16:17], v[0:1]
	v_pk_mul_f32 v[0:1], v[2:3], v[14:15]
	v_cvt_pk_bf16_f32 v2, v4, v5
	v_lshlrev_b64 v[4:5], 12, v[24:25]
	v_pk_fma_f32 v[6:7], v[6:7], v[12:13], v[0:1]
	v_lshl_add_u64 v[4:5], s[8:9], 0, v[4:5]
	v_cvt_pk_bf16_f32 v0, v8, v9
	v_cvt_pk_bf16_f32 v1, v10, v11
	v_cvt_pk_bf16_f32 v3, v6, v7
	v_lshl_add_u64 v[4:5], v[4:5], 0, v[80:81]
	global_store_dwordx4 v[4:5], v[0:3], off
	s_cbranch_vccz .LBB0_1382
	s_waitcnt vmcnt(0)
	s_cmpk_gt_u32 s3, 0xff
	s_cbranch_scc1 .LBB0_1389
	s_barrier
